# A-attention row sums moved from ones-MFMA to VALU f32 adds
# baseline (speedup 1.0000x reference)
; #define LAS __attribute__((address_space(3)))
; template <bool TRACK> ...
;     ...
;             for (int d = 0; d < 4; ++d) { kf[2 * d] = *(const LAS bf16x8*)(Kbuf + (r32 * 72 + d * 16 + hi * 8) * 2); kf[2 * d + 1] = *(const LAS bf16x8*)(Kbuf + ((32 + r32) * 72 + d * 16 + hi * 8) * 2); }
;             __builtin_amdgcn_sched_barrier(0);
; #pragma unroll
;             for (int d = 0; d < 4; ++d) {
;                 s0 = __builtin_amdgcn_mfma_f32_32x32x16_bf16(kf[2 * d], qf[d], s0, 0, 0, 0);
;                 s1 = __builtin_amdgcn_mfma_f32_32x32x16_bf16(kf[2 * d + 1], qf[d], s1, 0, 0, 0);
;             }
; #pragma unroll
;             for (int kc = 0; kc < 2; ++kc) {
;                 const LAS unsigned char* vp0 = Vbuf + (r32 * 68 + kc * 16 + 4 * hi) * 2; const LAS unsigned char* vp1 = vp0 + 32 * 68 * 2;
;                 vq[4 * kc] = *(const LAS u32x2*)vp0; vq[4 * kc + 1] = *(const LAS u32x2*)(vp0 + 16); vq[4 * kc + 2] = *(const LAS u32x2*)vp1; vq[4 * kc + 3] = *(const LAS u32x2*)(vp1 + 16); }
;             __builtin_amdgcn_sched_barrier(0);
;             } else {
; #pragma unroll
;             for (int d = 0; d < 4; ++d) {
;                 const bf16x8 a0 = *(const LAS bf16x8*)(Kbuf + (r32 * 72 + d * 16 + hi * 8) * 2);
;                 const bf16x8 a1 = *(const LAS bf16x8*)(Kbuf + ((32 + r32) * 72 + d * 16 + hi * 8) * 2);
;                 s0 = __builtin_amdgcn_mfma_f32_32x32x16_bf16(a0, qf[d], s0, 0, 0, 0);
;                 s1 = __builtin_amdgcn_mfma_f32_32x32x16_bf16(a1, qf[d], s1, 0, 0, 0);
;             }
;             }
;             if (mt) { const int qpos = qstart + wave * 32 + r32;
; #pragma unroll
;                 for (int r = 0; r < 16; ++r) { const int d0 = qpos - (kpos0 + crow(r, hi)); if (d0 > 128 || d0 < -128) s0[r] = -INFINITY; const int d1 = d0 - 32; if (d1 > 128 || d1 < -128) s1[r] = -INFINITY; } }
;             if (TRACK) {
;             float mx = fmaxf(fmaxf(s0[0], s1[0]), s0[1]);
; #pragma unroll
;             for (int r = 1; r < 15; r += 2) mx = fmaxf(fmaxf(mx, s1[r]), fmaxf(fmaxf(s0[r + 1], s1[r + 1]), s0[r + 2 < 16 ? r + 2 : 15]));
;             mx = fmaxf(mx, s1[15]);
;             mx = fmaxf(mx, __shfl_xor(mx, 32));
;             if (__any(mx > ATT_THR)) {
;                 const float dl = fmaxf(mx, 0.f); m += dl; const float alpha = __builtin_amdgcn_exp2f(-dl); lsum *= alpha;
; #pragma unroll
.LBB0_167:
	global_load_dwordx4 v[98:101], v[114:115], off
	global_load_dwordx4 v[102:105], v[116:117], off
	s_and_b32 s21, s20, 1
	s_mul_i32 s22, s21, 0x4800
	s_add_i32 s22, s22, 0
	v_add_u32_e32 v0, s22, v204
	v_add_u32_e32 v54, s22, v202
	ds_read_b128 v[50:53], v0
	ds_read_b128 v[106:109], v0 offset:32
	ds_read_b128 v[66:69], v54
	ds_read_b128 v[110:113], v54 offset:32
	ds_read_b128 v[118:121], v0 offset:64
	ds_read_b128 v[158:161], v0 offset:96
	ds_read_b128 v[206:209], v54 offset:64
	ds_read_b128 v[210:213], v54 offset:96
	s_add_i32 s20, s20, 1
	s_waitcnt lgkmcnt(7)
	v_mfma_f32_32x32x16_bf16 v[50:65], v[50:53], v[94:97], 0
	v_add3_u32 v0, s22, v199, v200
	v_add_u32_e32 v123, 0x2000, v0
	v_add_u32_e32 v0, 0x3000, v0
	s_waitcnt lgkmcnt(5)
	v_mfma_f32_32x32x16_bf16 v[66:81], v[66:69], v[94:97], 0
	v_mfma_f32_32x32x16_bf16 v[50:65], v[106:109], v[90:93], v[50:65]
	s_waitcnt lgkmcnt(4)
	v_mfma_f32_32x32x16_bf16 v[66:81], v[110:113], v[90:93], v[66:81]
	s_waitcnt lgkmcnt(3)
	v_mfma_f32_32x32x16_bf16 v[50:65], v[118:121], v[86:89], v[50:65]
	ds_read2_b64 v[118:121], v123 offset0:128 offset1:130
	ds_read2_b64 v[106:109], v123 offset0:132 offset1:134
	s_waitcnt lgkmcnt(3)
	v_mfma_f32_32x32x16_bf16 v[66:81], v[206:209], v[86:89], v[66:81]
	v_mfma_f32_32x32x16_bf16 v[50:65], v[158:161], v[82:85], v[50:65]
	ds_read2_b64 v[158:161], v0 offset0:160 offset1:162
	ds_read2_b64 v[110:113], v0 offset0:164 offset1:166
	s_waitcnt lgkmcnt(4)
	v_mfma_f32_32x32x16_bf16 v[66:81], v[210:213], v[82:85], v[66:81]
	s_nop 11
	v_exp_f32_e32 v66, v66
	v_exp_f32_e32 v67, v67
	v_add_f32_e32 v34, v34, v66
	v_exp_f32_e32 v68, v68
	v_add_f32_e32 v35, v35, v67
	v_exp_f32_e32 v69, v69
	v_add_f32_e32 v36, v36, v68
	v_exp_f32_e32 v54, v54
	v_add_f32_e32 v37, v37, v69
	v_exp_f32_e32 v55, v55
	v_add_f32_e32 v34, v34, v54
	v_exp_f32_e32 v129, v60
	v_add_f32_e32 v35, v35, v55
	v_cvt_pk_bf16_f32 v60, v54, v55
	v_add_f32_e32 v36, v36, v129
	v_cvt_pk_bf16_f32 v54, v66, v67
	v_cvt_pk_bf16_f32 v55, v68, v69
	v_exp_f32_e32 v50, v50
	v_exp_f32_e32 v51, v51
	v_add_f32_e32 v37, v37, v50
	v_exp_f32_e32 v52, v52
	v_add_f32_e32 v34, v34, v51
	v_exp_f32_e32 v53, v53
	v_add_f32_e32 v35, v35, v52
	v_exp_f32_e32 v56, v56
	v_add_f32_e32 v36, v36, v53
	v_exp_f32_e32 v57, v57
	v_add_f32_e32 v37, v37, v56
	v_exp_f32_e32 v125, v58
	v_add_f32_e32 v34, v34, v57
	v_exp_f32_e32 v127, v59
	v_add_f32_e32 v35, v35, v125
	v_exp_f32_e32 v131, v61
	v_add_f32_e32 v36, v36, v127
	v_cvt_pk_bf16_f32 v58, v50, v51
	v_add_f32_e32 v37, v37, v131
	v_cvt_pk_bf16_f32 v59, v52, v53
	v_cvt_pk_bf16_f32 v61, v56, v57
	v_exp_f32_e32 v133, v62
	v_exp_f32_e32 v135, v63
	v_add_f32_e32 v34, v34, v133
	s_waitcnt lgkmcnt(3)
	v_add_f32_e32 v35, v35, v135
	v_mfma_f32_32x32x16_bf16 v[2:17], v[118:121], v[58:61], v[2:17]
	v_exp_f32_e32 v157, v64
	v_exp_f32_e32 v65, v65
	v_add_f32_e32 v36, v36, v157
	v_cvt_pk_bf16_f32 v62, v125, v127
	v_add_f32_e32 v37, v37, v65
	v_cvt_pk_bf16_f32 v63, v129, v131
	v_cvt_pk_bf16_f32 v64, v133, v135
	v_cvt_pk_bf16_f32 v65, v157, v65
	v_exp_f32_e32 v70, v70
	s_waitcnt lgkmcnt(1)
	v_add_f32_e32 v34, v34, v70
	v_mfma_f32_32x32x16_bf16 v[18:33], v[158:161], v[58:61], v[18:33]
	v_exp_f32_e32 v71, v71
	v_exp_f32_e32 v72, v72
	v_add_f32_e32 v35, v35, v71
	v_exp_f32_e32 v73, v73
	v_add_f32_e32 v36, v36, v72
	v_exp_f32_e32 v74, v74
	v_add_f32_e32 v37, v37, v73
	v_cvt_pk_bf16_f32 v56, v70, v71
	v_add_f32_e32 v34, v34, v74
	v_exp_f32_e32 v75, v75
	v_cvt_pk_bf16_f32 v57, v72, v73
	v_add_f32_e32 v35, v35, v75
	v_exp_f32_e32 v76, v76
	v_exp_f32_e32 v77, v77
	v_add_f32_e32 v36, v36, v76
	v_exp_f32_e32 v78, v78
	v_add_f32_e32 v37, v37, v77
	v_exp_f32_e32 v79, v79
	v_add_f32_e32 v34, v34, v78
	v_exp_f32_e32 v80, v80
	v_add_f32_e32 v35, v35, v79
	v_exp_f32_e32 v81, v81
	v_add_f32_e32 v36, v36, v80
	v_cvt_pk_bf16_f32 v50, v74, v75
	v_add_f32_e32 v37, v37, v81
	v_mfma_f32_32x32x16_bf16 v[2:17], v[106:109], v[62:65], v[2:17]
	v_cvt_pk_bf16_f32 v51, v76, v77
	v_cvt_pk_bf16_f32 v52, v78, v79
	v_cvt_pk_bf16_f32 v53, v80, v81
	s_xor_b32 s21, s21, 1
	s_mulk_i32 s21, 0x4800
	s_add_i32 s21, s21, 0
	v_lshl_add_u64 v[114:115], v[114:115], 0, s[4:5]
	s_waitcnt lgkmcnt(0)
	v_mfma_f32_32x32x16_bf16 v[18:33], v[110:113], v[62:65], v[18:33]
	v_lshl_add_u64 v[116:117], v[116:117], 0, s[38:39]
	s_cmp_lg_u32 s20, 35
	ds_read2_b64 v[58:61], v0 offset0:168 offset1:170
	ds_read2_b64 v[62:65], v123 offset0:136 offset1:138
	ds_read2_b64 v[70:73], v123 offset0:140 offset1:142
	s_waitcnt lgkmcnt(1)
	v_mfma_f32_32x32x16_bf16 v[2:17], v[62:65], v[54:57], v[2:17]
	v_mfma_f32_32x32x16_bf16 v[18:33], v[58:61], v[54:57], v[18:33]
	ds_read2_b64 v[54:57], v0 offset0:172 offset1:174
	v_add_u32_e32 v0, s21, v201
	s_waitcnt lgkmcnt(1)
	v_mfma_f32_32x32x16_bf16 v[2:17], v[70:73], v[50:53], v[2:17]
	s_waitcnt lgkmcnt(0)
	v_mfma_f32_32x32x16_bf16 v[18:33], v[54:57], v[50:53], v[18:33]
	v_add_u32_e32 v50, s21, v203
	v_add_u32_e32 v50, 0x2400, v50
	s_waitcnt vmcnt(1)
	ds_write_b128 v0, v[98:101]
	s_waitcnt vmcnt(0)
	ds_write2_b64 v50, v[102:103], v[104:105] offset1:1
	s_waitcnt lgkmcnt(0)
	s_barrier
	s_cbranch_scc1 .LBB0_167
; #define LAS __attribute__((address_space(3)))
; template <bool TRACK> ...
;     ...
;             for (int kc = 0; kc < 4; ++kc) {
;                 u32x2 a, bq, c2, d2;
;                 if (!TRACK && kc < 2) { a = vq[4 * kc]; bq = vq[4 * kc + 1]; c2 = vq[4 * kc + 2]; d2 = vq[4 * kc + 3]; }
;                 else { const LAS unsigned char* vp0 = Vbuf + (r32 * 68 + kc * 16 + 4 * hi) * 2; const LAS unsigned char* vp1 = vp0 + 32 * 68 * 2;
;                     a = *(const LAS u32x2*)vp0; bq = *(const LAS u32x2*)(vp0 + 16); c2 = *(const LAS u32x2*)vp1; d2 = *(const LAS u32x2*)(vp1 + 16); }
;                 const bf16x8 v0 = __builtin_bit_cast(bf16x8, ((u32x4){a.x, a.y, bq.x, bq.y})), v1 = __builtin_bit_cast(bf16x8, ((u32x4){c2.x, c2.y, d2.x, d2.y}));
;                 o0 = __builtin_amdgcn_mfma_f32_32x32x16_bf16(v0, pk[kc], o0, 0, 0, 0);
;                 o1 = __builtin_amdgcn_mfma_f32_32x32x16_bf16(v1, pk[kc], o1, 0, 0, 0);
;                 if (!TRACK) lacc = __builtin_amdgcn_mfma_f32_32x32x16_bf16(ones, pk[kc], lacc, 0, 0, 0);
;             }
;         }
;         if (j + 1 < nt) { LAS unsigned char* nb = lds + (cur ^ 1) * 18432; *(LAS u32x4*)(nb + (srow * 72 + sc * 8) * 2) = kreg; LAS u32x2* vw_ = (LAS u32x2*)(nb + 9216 + (srow * 68 + sc * 8) * 2); vw_[0] = (u32x2){vreg.x, vreg.y}; vw_[1] = (u32x2){vreg.z, vreg.w}; }
;         __syncthreads();
;     }
;     const float ltot = TRACK ? lsum + __shfl_xor(lsum, 32) : lacc[0]; const float inv = 1.0f / ltot;
	v_add_u32_e32 v0, 0, v204
	v_add_u32_e32 v54, 0, v202
	ds_read_b128 v[50:53], v0 offset:18432
	ds_read_b128 v[98:101], v0 offset:18464
	ds_read_b128 v[66:69], v54 offset:18432
	ds_read_b128 v[102:105], v54 offset:18464
	ds_read_b128 v[106:109], v0 offset:18496
	ds_read_b128 v[110:113], v0 offset:18528
	ds_read_b128 v[114:117], v54 offset:18496
	ds_read_b128 v[118:121], v54 offset:18528
	s_waitcnt lgkmcnt(7)
	v_mfma_f32_32x32x16_bf16 v[50:65], v[50:53], v[94:97], 0
	v_add3_u32 v0, 0, v199, v200
	s_waitcnt lgkmcnt(5)
	v_mfma_f32_32x32x16_bf16 v[66:81], v[66:69], v[94:97], 0
	v_mfma_f32_32x32x16_bf16 v[50:65], v[98:101], v[90:93], v[50:65]
	s_waitcnt lgkmcnt(4)
	v_mfma_f32_32x32x16_bf16 v[66:81], v[102:105], v[90:93], v[66:81]
	v_add_u32_e32 v102, 0x6800, v0
	v_add_u32_e32 v0, 0x7800, v0
	ds_read2_b64 v[94:97], v102 offset0:128 offset1:130
	ds_read2_b64 v[90:93], v102 offset0:132 offset1:134
	s_waitcnt lgkmcnt(5)
	v_mfma_f32_32x32x16_bf16 v[50:65], v[106:109], v[86:89], v[50:65]
	s_waitcnt lgkmcnt(3)
	v_mfma_f32_32x32x16_bf16 v[66:81], v[114:117], v[86:89], v[66:81]
	ds_read2_b64 v[98:101], v0 offset0:160 offset1:162
	ds_read2_b64 v[86:89], v0 offset0:164 offset1:166
	v_mfma_f32_32x32x16_bf16 v[50:65], v[110:113], v[82:85], v[50:65]
	s_waitcnt lgkmcnt(4)
	v_mfma_f32_32x32x16_bf16 v[66:81], v[118:121], v[82:85], v[66:81]
	s_nop 9
	v_exp_f32_e32 v50, v50
	s_nop 0
	v_add_f32_e32 v34, v34, v50
	v_exp_f32_e32 v66, v66
	v_exp_f32_e32 v51, v51
	v_add_f32_e32 v35, v35, v66
	v_exp_f32_e32 v67, v67
	v_add_f32_e32 v36, v36, v51
	v_exp_f32_e32 v52, v52
	v_add_f32_e32 v37, v37, v67
	v_exp_f32_e32 v68, v68
	v_add_f32_e32 v34, v34, v52
	v_exp_f32_e32 v53, v53
	v_add_f32_e32 v35, v35, v68
	v_exp_f32_e32 v69, v69
	v_add_f32_e32 v36, v36, v53
	v_exp_f32_e32 v54, v54
	v_add_f32_e32 v37, v37, v69
	v_exp_f32_e32 v55, v55
	v_add_f32_e32 v34, v34, v54
	v_exp_f32_e32 v58, v58
	v_add_f32_e32 v35, v35, v55
	v_exp_f32_e32 v59, v59
	v_add_f32_e32 v36, v36, v58
	v_cvt_pk_bf16_f32 v50, v50, v51
	v_add_f32_e32 v37, v37, v59
	v_cvt_pk_bf16_f32 v51, v52, v53
	v_cvt_pk_bf16_f32 v52, v54, v55
	v_cvt_pk_bf16_f32 v54, v58, v59
	v_cvt_pk_bf16_f32 v58, v66, v67
	v_cvt_pk_bf16_f32 v59, v68, v69
	v_exp_f32_e32 v56, v56
	v_exp_f32_e32 v57, v57
	v_add_f32_e32 v34, v34, v56
	v_exp_f32_e32 v60, v60
	v_add_f32_e32 v35, v35, v57
	v_exp_f32_e32 v61, v61
	v_add_f32_e32 v36, v36, v60
	v_cvt_pk_bf16_f32 v53, v56, v57
	v_add_f32_e32 v37, v37, v61
	v_exp_f32_e32 v62, v62
	v_exp_f32_e32 v63, v63
	v_add_f32_e32 v34, v34, v62
	v_exp_f32_e32 v64, v64
	v_add_f32_e32 v35, v35, v63
	v_exp_f32_e32 v65, v65
	v_add_f32_e32 v36, v36, v64
	v_cvt_pk_bf16_f32 v55, v60, v61
	v_add_f32_e32 v37, v37, v65
	v_cvt_pk_bf16_f32 v56, v62, v63
	v_exp_f32_e32 v70, v70
	v_cvt_pk_bf16_f32 v57, v64, v65
	v_add_f32_e32 v34, v34, v70
	v_exp_f32_e32 v71, v71
	v_exp_f32_e32 v72, v72
	v_add_f32_e32 v35, v35, v71
	v_exp_f32_e32 v73, v73
	v_add_f32_e32 v36, v36, v72
	v_cvt_pk_bf16_f32 v60, v70, v71
	v_add_f32_e32 v37, v37, v73
	v_exp_f32_e32 v74, v74
	v_exp_f32_e32 v75, v75
	v_add_f32_e32 v34, v34, v74
	v_cvt_pk_bf16_f32 v61, v72, v73
	v_add_f32_e32 v35, v35, v75
	v_exp_f32_e32 v76, v76
	v_exp_f32_e32 v77, v77
	v_add_f32_e32 v36, v36, v76
	s_waitcnt lgkmcnt(3)
	v_add_f32_e32 v37, v37, v77
	v_mfma_f32_32x32x16_bf16 v[2:17], v[94:97], v[50:53], v[2:17]
	v_exp_f32_e32 v78, v78
	v_exp_f32_e32 v79, v79
	v_add_f32_e32 v34, v34, v78
	v_exp_f32_e32 v80, v80
	v_add_f32_e32 v35, v35, v79
	v_exp_f32_e32 v81, v81
	v_add_f32_e32 v36, v36, v80
	v_cvt_pk_bf16_f32 v62, v74, v75
	v_add_f32_e32 v37, v37, v81
	v_cvt_pk_bf16_f32 v63, v76, v77
	v_cvt_pk_bf16_f32 v64, v78, v79
	s_waitcnt lgkmcnt(1)
	v_mfma_f32_32x32x16_bf16 v[18:33], v[98:101], v[50:53], v[18:33]
	v_cvt_pk_bf16_f32 v65, v80, v81
	v_readlane_b32 s89, v248, 3
	v_mfma_f32_32x32x16_bf16 v[2:17], v[90:93], v[54:57], v[2:17]
	s_waitcnt lgkmcnt(0)
	v_mfma_f32_32x32x16_bf16 v[18:33], v[86:89], v[54:57], v[18:33]
	ds_read2_b64 v[50:53], v0 offset0:168 offset1:170
	ds_read2_b64 v[54:57], v102 offset0:136 offset1:138
	ds_read2_b64 v[70:73], v102 offset0:140 offset1:142
	s_waitcnt lgkmcnt(1)
	v_mfma_f32_32x32x16_bf16 v[2:17], v[54:57], v[58:61], v[2:17]
	v_mfma_f32_32x32x16_bf16 v[18:33], v[50:53], v[58:61], v[18:33]
	ds_read2_b64 v[50:53], v0 offset0:172 offset1:174
	s_nop 7
	v_add_f32_e32 v34, v34, v35
	v_add_f32_e32 v36, v36, v37
	s_nop 0
	v_add_f32_e32 v34, v34, v36
	s_nop 0
	ds_bpermute_b32 v35, v188, v34
	s_waitcnt lgkmcnt(0)
	v_add_f32_e32 v34, v34, v35
	s_nop 0
	v_div_scale_f32 v0, s[20:21], v34, v34, 1.0
	v_rcp_f32_e32 v35, v0
	s_waitcnt lgkmcnt(0)
	s_barrier
; #define LAS __attribute__((address_space(3)))
; __device__ __forceinline__ unsigned pk2(float lo, float hi) { f32x2_t v = {lo, hi}; bf16x2_t b = __builtin_convertvector(v, bf16x2_t); return __builtin_bit_cast(unsigned, b); }
; __device__ __forceinline__ float silu_f(float v) { return v * __builtin_amdgcn_rcpf(1.0f + __expf(-v)); }
; template <bool TRACK> ...
;     ...
;     const float ltot = TRACK ? lsum + __shfl_xor(lsum, 32) : lacc[0]; const float inv = 1.0f / ltot;
;     {
;         LAS unsigned char* scr = lds + 40960 + wave * 8704;
; #pragma unroll
;         for (int dh = 0; dh < 2; ++dh)
; #pragma unroll
;             for (int rg = 0; rg < 4; ++rg) { const int d = dh * 32 + 8 * rg + 4 * hi;
;                 f32x4 ov; ov.x = (dh == 0 ? o0[4 * rg] : o1[4 * rg]) * inv; ov.y = (dh == 0 ? o0[4 * rg + 1] : o1[4 * rg + 1]) * inv; ov.z = (dh == 0 ? o0[4 * rg + 2] : o1[4 * rg + 2]) * inv; ov.w = (dh == 0 ? o0[4 * rg + 3] : o1[4 * rg + 3]) * inv;
;                 *(LAS f32x4*)(scr + r32 * 272 + d * 4) = ov; }
;         const int pc = lane & 7;
; #pragma unroll
;         for (int i = 0; i < 4; ++i) { const int rw = i * 8 + (lane >> 3), row = wave * 32 + rw;
;             const f32x4 oa = *(const LAS f32x4*)(scr + rw * 272 + pc * 32), ob = *(const LAS f32x4*)(scr + rw * 272 + pc * 32 + 16);
;             float gv[8]; unpack8(*(const u32x4*)(gate + (size_t)row * INW + 8 * pc), gv);
;             u32x4 w; w.x = pk2(oa.x * silu_f(gv[0]), oa.y * silu_f(gv[1])); w.y = pk2(oa.z * silu_f(gv[2]), oa.w * silu_f(gv[3]));
;             w.z = pk2(ob.x * silu_f(gv[4]), ob.y * silu_f(gv[5])); w.w = pk2(ob.z * silu_f(gv[6]), ob.w * silu_f(gv[7]));
;             *(u32x4*)(outp + (size_t)row * DM + 8 * pc) = w; }
	v_mfma_f32_32x32x16_bf16 v[2:17], v[70:73], v[62:65], v[2:17]
	v_fma_f32 v36, -v0, v35, 1.0
	v_fmac_f32_e32 v35, v36, v35
	v_div_scale_f32 v36, vcc, 1.0, v34, 1.0
	v_mul_f32_e32 v37, v36, v35
	v_fma_f32 v38, -v0, v37, v36
	v_fmac_f32_e32 v37, v38, v35
	v_mfma_f32_32x32x16_bf16 v[18:33], v[50:53], v[62:65], v[18:33]
	v_fma_f32 v0, -v0, v37, v36
	v_div_fmas_f32 v0, v0, v35, v37
	v_div_fixup_f32 v0, v0, v34, 1.0
	s_nop 1
	v_mul_f32_e64 v2, v2, v0
	v_mul_f32_e64 v3, v3, v0
	v_pk_mul_f32 v[4:5], v[4:5], v[0:1] op_sel_hi:[1,0]
	v_add_u32_e32 v34, v198, v156
	ds_write_b128 v34, v[2:5] offset:40960
	v_pk_mul_f32 v[2:3], v[6:7], v[0:1] op_sel_hi:[1,0]
	v_pk_mul_f32 v[4:5], v[8:9], v[0:1] op_sel_hi:[1,0]
	ds_write_b128 v34, v[2:5] offset:40992
	v_pk_mul_f32 v[2:3], v[10:11], v[0:1] op_sel_hi:[1,0]
	v_pk_mul_f32 v[4:5], v[12:13], v[0:1] op_sel_hi:[1,0]
	ds_write_b128 v34, v[2:5] offset:41024
	v_pk_mul_f32 v[2:3], v[14:15], v[0:1] op_sel_hi:[1,0]
	v_pk_mul_f32 v[4:5], v[16:17], v[0:1] op_sel_hi:[1,0]
	ds_write_b128 v34, v[2:5] offset:41056
	v_pk_mul_f32 v[2:3], v[18:19], v[0:1] op_sel_hi:[1,0]
	v_pk_mul_f32 v[4:5], v[20:21], v[0:1] op_sel_hi:[1,0]
	ds_write_b128 v34, v[2:5] offset:41088
	v_pk_mul_f32 v[2:3], v[22:23], v[0:1] op_sel_hi:[1,0]
	v_pk_mul_f32 v[4:5], v[24:25], v[0:1] op_sel_hi:[1,0]
	ds_write_b128 v34, v[2:5] offset:41120
	v_pk_mul_f32 v[2:3], v[26:27], v[0:1] op_sel_hi:[1,0]
	v_pk_mul_f32 v[4:5], v[28:29], v[0:1] op_sel_hi:[1,0]
	ds_write_b128 v34, v[2:5] offset:41152
	v_pk_mul_f32 v[2:3], v[30:31], v[0:1] op_sel_hi:[1,0]
	v_pk_mul_f32 v[4:5], v[32:33], v[0:1] op_sel_hi:[1,0]
	ds_write_b128 v34, v[2:5] offset:41184
	v_add_u32_e32 v0, v192, v193
	ds_read_b128 v[6:9], v0 offset:40960
	ds_read_b128 v[2:5], v0 offset:40976
	global_load_dwordx4 v[10:13], v[154:155], off offset:1280
	s_waitcnt vmcnt(0)
	v_lshlrev_b32_e32 v14, 16, v10
	v_and_b32_e32 v15, 0xffff0000, v10
	v_mul_f32_e32 v10, 0xbfb8aa3b, v14
	v_exp_f32_e32 v10, v10
	s_nop 0
	v_add_f32_e32 v10, 1.0, v10
	v_rcp_f32_e32 v16, v10
	v_mul_f32_e32 v10, 0xbfb8aa3b, v15
	v_exp_f32_e32 v10, v10
	s_nop 0
	v_add_f32_e32 v10, 1.0, v10
	v_rcp_f32_e32 v17, v10
	v_lshlrev_b32_e32 v10, 16, v11
	v_and_b32_e32 v11, 0xffff0000, v11
	v_pk_mul_f32 v[14:15], v[16:17], v[14:15]
	s_waitcnt lgkmcnt(1)
	v_pk_mul_f32 v[6:7], v[6:7], v[14:15]
	s_nop 0
	v_cvt_pk_bf16_f32 v6, v6, v7
	v_mul_f32_e32 v7, 0xbfb8aa3b, v10
	v_exp_f32_e32 v7, v7
	s_nop 0
	v_add_f32_e32 v7, 1.0, v7
	v_rcp_f32_e32 v14, v7
	v_mul_f32_e32 v7, 0xbfb8aa3b, v11
	v_exp_f32_e32 v7, v7
	s_nop 0
	v_add_f32_e32 v7, 1.0, v7
	v_rcp_f32_e32 v15, v7
	s_nop 0
	v_pk_mul_f32 v[10:11], v[14:15], v[10:11]
	s_nop 0
	v_pk_mul_f32 v[8:9], v[8:9], v[10:11]
	s_nop 0
	v_cvt_pk_bf16_f32 v7, v8, v9
	v_lshlrev_b32_e32 v8, 16, v12
	v_and_b32_e32 v9, 0xffff0000, v12
	v_mul_f32_e32 v10, 0xbfb8aa3b, v8
	v_mul_f32_e32 v11, 0xbfb8aa3b, v9
	v_exp_f32_e32 v10, v10
	v_exp_f32_e32 v11, v11
	v_add_f32_e32 v10, 1.0, v10
	v_add_f32_e32 v11, 1.0, v11
	v_rcp_f32_e32 v10, v10
	v_rcp_f32_e32 v11, v11
	s_nop 0
	v_pk_mul_f32 v[8:9], v[10:11], v[8:9]
	s_waitcnt lgkmcnt(0)
	v_pk_mul_f32 v[2:3], v[2:3], v[8:9]
	s_nop 0
	v_cvt_pk_bf16_f32 v8, v2, v3
	v_lshlrev_b32_e32 v2, 16, v13
	v_mul_f32_e32 v9, 0xbfb8aa3b, v2
	v_exp_f32_e32 v9, v9
	v_and_b32_e32 v3, 0xffff0000, v13
	v_add_f32_e32 v9, 1.0, v9
	v_rcp_f32_e32 v10, v9
	v_mul_f32_e32 v9, 0xbfb8aa3b, v3
	v_exp_f32_e32 v9, v9
	s_nop 0
	v_add_f32_e32 v9, 1.0, v9
	v_rcp_f32_e32 v11, v9
	s_nop 0
	v_pk_mul_f32 v[2:3], v[10:11], v[2:3]
	s_nop 0
	v_pk_mul_f32 v[2:3], v[4:5], v[2:3]
	s_nop 0
	v_cvt_pk_bf16_f32 v9, v2, v3
	global_store_dwordx4 v[152:153], v[6:9], off
	ds_read_b128 v[6:9], v0 offset:43136
	ds_read_b128 v[2:5], v0 offset:43152
	global_load_dwordx4 v[10:13], v[150:151], off offset:1280
	s_waitcnt vmcnt(0)
	v_lshlrev_b32_e32 v14, 16, v10
	v_and_b32_e32 v15, 0xffff0000, v10
	v_mul_f32_e32 v10, 0xbfb8aa3b, v14
	v_exp_f32_e32 v10, v10
	s_nop 0
	v_add_f32_e32 v10, 1.0, v10
	v_rcp_f32_e32 v16, v10
	v_mul_f32_e32 v10, 0xbfb8aa3b, v15
	v_exp_f32_e32 v10, v10
	s_nop 0
	v_add_f32_e32 v10, 1.0, v10
	v_rcp_f32_e32 v17, v10
	v_lshlrev_b32_e32 v10, 16, v11
	v_and_b32_e32 v11, 0xffff0000, v11
	v_pk_mul_f32 v[14:15], v[16:17], v[14:15]
	s_waitcnt lgkmcnt(1)
	v_pk_mul_f32 v[6:7], v[6:7], v[14:15]
	s_nop 0
	v_cvt_pk_bf16_f32 v6, v6, v7
	v_mul_f32_e32 v7, 0xbfb8aa3b, v10
	v_exp_f32_e32 v7, v7
	s_nop 0
	v_add_f32_e32 v7, 1.0, v7
	v_rcp_f32_e32 v14, v7
	v_mul_f32_e32 v7, 0xbfb8aa3b, v11
	v_exp_f32_e32 v7, v7
	s_nop 0
	v_add_f32_e32 v7, 1.0, v7
	v_rcp_f32_e32 v15, v7
	s_nop 0
	v_pk_mul_f32 v[10:11], v[14:15], v[10:11]
	s_nop 0
	v_pk_mul_f32 v[8:9], v[8:9], v[10:11]
	s_nop 0
	v_cvt_pk_bf16_f32 v7, v8, v9
	v_lshlrev_b32_e32 v8, 16, v12
	v_and_b32_e32 v9, 0xffff0000, v12
	v_mul_f32_e32 v10, 0xbfb8aa3b, v8
	v_mul_f32_e32 v11, 0xbfb8aa3b, v9
	v_exp_f32_e32 v10, v10
	v_exp_f32_e32 v11, v11
	v_add_f32_e32 v10, 1.0, v10
	v_add_f32_e32 v11, 1.0, v11
	v_rcp_f32_e32 v10, v10
	v_rcp_f32_e32 v11, v11
	s_nop 0
	v_pk_mul_f32 v[8:9], v[10:11], v[8:9]
	s_waitcnt lgkmcnt(0)
; #define LAS __attribute__((address_space(3)))
; __device__ __forceinline__ unsigned pk2(float lo, float hi) { f32x2_t v = {lo, hi}; bf16x2_t b = __builtin_convertvector(v, bf16x2_t); return __builtin_bit_cast(unsigned, b); }
; __device__ __forceinline__ float silu_f(float v) { return v * __builtin_amdgcn_rcpf(1.0f + __expf(-v)); }
; template <bool TRACK> ...
;     ...
;         const int pc = lane & 7;
; #pragma unroll
;         for (int i = 0; i < 4; ++i) { const int rw = i * 8 + (lane >> 3), row = wave * 32 + rw;
;             const f32x4 oa = *(const LAS f32x4*)(scr + rw * 272 + pc * 32), ob = *(const LAS f32x4*)(scr + rw * 272 + pc * 32 + 16);
;             float gv[8]; unpack8(*(const u32x4*)(gate + (size_t)row * INW + 8 * pc), gv);
;             u32x4 w; w.x = pk2(oa.x * silu_f(gv[0]), oa.y * silu_f(gv[1])); w.y = pk2(oa.z * silu_f(gv[2]), oa.w * silu_f(gv[3]));
;             w.z = pk2(ob.x * silu_f(gv[4]), ob.y * silu_f(gv[5])); w.w = pk2(ob.z * silu_f(gv[6]), ob.w * silu_f(gv[7]));
;             *(u32x4*)(outp + (size_t)row * DM + 8 * pc) = w; }
	v_pk_mul_f32 v[2:3], v[2:3], v[8:9]
	s_nop 0
	v_cvt_pk_bf16_f32 v8, v2, v3
	v_lshlrev_b32_e32 v2, 16, v13
	v_mul_f32_e32 v9, 0xbfb8aa3b, v2
	v_exp_f32_e32 v9, v9
	v_and_b32_e32 v3, 0xffff0000, v13
	v_add_f32_e32 v9, 1.0, v9
	v_rcp_f32_e32 v10, v9
	v_mul_f32_e32 v9, 0xbfb8aa3b, v3
	v_exp_f32_e32 v9, v9
	s_nop 0
	v_add_f32_e32 v9, 1.0, v9
	v_rcp_f32_e32 v11, v9
	s_nop 0
	v_pk_mul_f32 v[2:3], v[10:11], v[2:3]
	s_nop 0
	v_pk_mul_f32 v[2:3], v[4:5], v[2:3]
	s_nop 0
	v_cvt_pk_bf16_f32 v9, v2, v3
	global_store_dwordx4 v[144:145], v[6:9], off
	ds_read_b128 v[6:9], v0 offset:45312
	ds_read_b128 v[2:5], v0 offset:45328
	global_load_dwordx4 v[10:13], v[142:143], off offset:1280
	s_waitcnt vmcnt(0)
	v_lshlrev_b32_e32 v14, 16, v10
	v_and_b32_e32 v15, 0xffff0000, v10
	v_mul_f32_e32 v10, 0xbfb8aa3b, v14
	v_exp_f32_e32 v10, v10
	s_nop 0
	v_add_f32_e32 v10, 1.0, v10
	v_rcp_f32_e32 v16, v10
	v_mul_f32_e32 v10, 0xbfb8aa3b, v15
	v_exp_f32_e32 v10, v10
	s_nop 0
	v_add_f32_e32 v10, 1.0, v10
	v_rcp_f32_e32 v17, v10
	v_lshlrev_b32_e32 v10, 16, v11
	v_and_b32_e32 v11, 0xffff0000, v11
	v_pk_mul_f32 v[14:15], v[16:17], v[14:15]
	s_waitcnt lgkmcnt(1)
	v_pk_mul_f32 v[6:7], v[6:7], v[14:15]
	s_nop 0
	v_cvt_pk_bf16_f32 v6, v6, v7
	v_mul_f32_e32 v7, 0xbfb8aa3b, v10
	v_exp_f32_e32 v7, v7
	s_nop 0
	v_add_f32_e32 v7, 1.0, v7
	v_rcp_f32_e32 v14, v7
	v_mul_f32_e32 v7, 0xbfb8aa3b, v11
	v_exp_f32_e32 v7, v7
	s_nop 0
	v_add_f32_e32 v7, 1.0, v7
	v_rcp_f32_e32 v15, v7
	s_nop 0
	v_pk_mul_f32 v[10:11], v[14:15], v[10:11]
	s_nop 0
	v_pk_mul_f32 v[8:9], v[8:9], v[10:11]
	s_nop 0
	v_cvt_pk_bf16_f32 v7, v8, v9
	v_lshlrev_b32_e32 v8, 16, v12
	v_and_b32_e32 v9, 0xffff0000, v12
	v_mul_f32_e32 v10, 0xbfb8aa3b, v8
	v_mul_f32_e32 v11, 0xbfb8aa3b, v9
	v_exp_f32_e32 v10, v10
	v_exp_f32_e32 v11, v11
	v_add_f32_e32 v10, 1.0, v10
	v_add_f32_e32 v11, 1.0, v11
	v_rcp_f32_e32 v10, v10
	v_rcp_f32_e32 v11, v11
	s_nop 0
	v_pk_mul_f32 v[8:9], v[10:11], v[8:9]
	s_waitcnt lgkmcnt(0)
	v_pk_mul_f32 v[2:3], v[2:3], v[8:9]
	s_nop 0
	v_cvt_pk_bf16_f32 v8, v2, v3
	v_lshlrev_b32_e32 v2, 16, v13
	v_mul_f32_e32 v9, 0xbfb8aa3b, v2
	v_exp_f32_e32 v9, v9
	v_and_b32_e32 v3, 0xffff0000, v13
	v_add_f32_e32 v9, 1.0, v9
	v_rcp_f32_e32 v10, v9
	v_mul_f32_e32 v9, 0xbfb8aa3b, v3
	v_exp_f32_e32 v9, v9
	s_nop 0
	v_add_f32_e32 v9, 1.0, v9
	v_rcp_f32_e32 v11, v9
	s_nop 0
	v_pk_mul_f32 v[2:3], v[10:11], v[2:3]
	s_nop 0
	v_pk_mul_f32 v[2:3], v[4:5], v[2:3]
	s_nop 0
	v_cvt_pk_bf16_f32 v9, v2, v3
	global_store_dwordx4 v[140:141], v[6:9], off
	ds_read_b128 v[6:9], v0 offset:47488
	ds_read_b128 v[2:5], v0 offset:47504
	global_load_dwordx4 v[10:13], v[138:139], off offset:1280
	s_waitcnt vmcnt(0)
	v_lshlrev_b32_e32 v14, 16, v10
	v_mul_f32_e32 v0, 0xbfb8aa3b, v14
	v_exp_f32_e32 v0, v0
	v_and_b32_e32 v15, 0xffff0000, v10
	v_lshlrev_b32_e32 v10, 16, v11
	v_and_b32_e32 v11, 0xffff0000, v11
	v_add_f32_e32 v0, 1.0, v0
	v_rcp_f32_e32 v16, v0
	v_mul_f32_e32 v0, 0xbfb8aa3b, v15
	v_exp_f32_e32 v0, v0
	s_nop 0
	v_add_f32_e32 v0, 1.0, v0
	v_rcp_f32_e32 v17, v0
	v_mul_f32_e32 v0, 0xbfb8aa3b, v10
	v_exp_f32_e32 v0, v0
	v_pk_mul_f32 v[14:15], v[16:17], v[14:15]
	s_waitcnt lgkmcnt(1)
	v_pk_mul_f32 v[6:7], v[6:7], v[14:15]
	v_add_f32_e32 v0, 1.0, v0
	v_rcp_f32_e32 v14, v0
	v_mul_f32_e32 v0, 0xbfb8aa3b, v11
	v_exp_f32_e32 v0, v0
	v_cvt_pk_bf16_f32 v6, v6, v7
	v_add_f32_e32 v0, 1.0, v0
	v_rcp_f32_e32 v15, v0
	s_nop 0
	v_pk_mul_f32 v[10:11], v[14:15], v[10:11]
	s_nop 0
	v_pk_mul_f32 v[8:9], v[8:9], v[10:11]
	s_nop 0
	v_cvt_pk_bf16_f32 v7, v8, v9
	v_lshlrev_b32_e32 v8, 16, v12
	v_mul_f32_e32 v0, 0xbfb8aa3b, v8
	v_exp_f32_e32 v0, v0
	v_and_b32_e32 v9, 0xffff0000, v12
	v_add_f32_e32 v0, 1.0, v0
	v_rcp_f32_e32 v10, v0
	v_mul_f32_e32 v0, 0xbfb8aa3b, v9
	v_exp_f32_e32 v0, v0
	s_nop 0
	v_add_f32_e32 v0, 1.0, v0
	v_rcp_f32_e32 v11, v0
	s_nop 0
	v_pk_mul_f32 v[8:9], v[10:11], v[8:9]
	s_waitcnt lgkmcnt(0)
	v_pk_mul_f32 v[2:3], v[2:3], v[8:9]
	s_nop 0
	v_cvt_pk_bf16_f32 v8, v2, v3
	v_lshlrev_b32_e32 v2, 16, v13
	v_mul_f32_e32 v0, 0xbfb8aa3b, v2
	v_exp_f32_e32 v0, v0
	v_and_b32_e32 v3, 0xffff0000, v13
	v_add_f32_e32 v0, 1.0, v0
	v_rcp_f32_e32 v10, v0
	v_mul_f32_e32 v0, 0xbfb8aa3b, v3
	v_exp_f32_e32 v0, v0
	s_nop 0
	v_add_f32_e32 v0, 1.0, v0
	v_rcp_f32_e32 v11, v0
	s_nop 0
	v_pk_mul_f32 v[2:3], v[10:11], v[2:3]
	s_nop 0
	v_pk_mul_f32 v[2:3], v[4:5], v[2:3]
	s_nop 0
	v_cvt_pk_bf16_f32 v9, v2, v3
	global_store_dwordx4 v[136:137], v[6:9], off
